# layer-1 out-proj epilogue fused with last residual add (x2 stored in place as bf16(x2*gg1)); final pass reads one stream
# baseline (speedup 1.0000x reference)
.LBB0_716:
	s_branch .Lfe_start
	v_lshl_or_b32 v166, s96, 8, v174
	v_ashrrev_i32_e32 v167, 31, v166
	v_lshl_add_u64 v[100:101], v[166:167], 2, s[44:45]
	global_load_dwordx4 v[104:107], v[100:101], off offset:16
	global_load_dwordx4 v[108:111], v[100:101], off
	global_load_dwordx4 v[96:99], v[100:101], off offset:528
	s_nop 0
	global_load_dwordx4 v[100:103], v[100:101], off offset:512
	v_lshl_add_u32 v170, s92, 8, v172
	v_ashrrev_i32_e32 v171, 31, v170
	v_lshlrev_b64 v[168:169], 12, v[170:171]
	v_lshl_add_u64 v[190:191], s[38:39], 0, v[168:169]
	v_lshlrev_b64 v[168:169], 1, v[166:167]
	v_lshl_add_u64 v[166:167], v[190:191], 0, v[168:169]
	s_mov_b64 s[10:11], 0x80000
	s_mov_b64 s[58:59], -1
	s_waitcnt vmcnt(0)
	v_pk_mul_f32 v[190:191], v[138:139], v[106:107]
	v_pk_mul_f32 v[142:143], v[142:143], v[110:111]
	v_pk_mul_f32 v[140:141], v[140:141], v[108:109]
	v_pk_mul_f32 v[138:139], v[136:137], v[104:105]
	v_cvt_pk_bf16_f32 v136, v140, v141
	v_cvt_pk_bf16_f32 v137, v142, v143
	v_pk_mul_f32 v[132:133], v[132:133], v[100:101]
	v_cvt_pk_bf16_f32 v138, v138, v139
	v_cvt_pk_bf16_f32 v139, v190, v191
	global_store_dwordx4 v[166:167], v[136:139], off
	v_pk_mul_f32 v[134:135], v[134:135], v[102:103]
	v_pk_mul_f32 v[126:127], v[126:127], v[110:111]
	v_pk_mul_f32 v[136:137], v[130:131], v[98:99]
	v_pk_mul_f32 v[130:131], v[128:129], v[96:97]
	v_cvt_pk_bf16_f32 v128, v132, v133
	v_cvt_pk_bf16_f32 v129, v134, v135
	v_pk_mul_f32 v[124:125], v[124:125], v[108:109]
	v_cvt_pk_bf16_f32 v130, v130, v131
	v_cvt_pk_bf16_f32 v131, v136, v137
	global_store_dwordx4 v[166:167], v[128:131], off offset:256
	v_pk_mul_f32 v[116:117], v[116:117], v[100:101]
	v_pk_mul_f32 v[118:119], v[118:119], v[102:103]
	v_or_b32_e32 v128, 16, v170
	v_ashrrev_i32_e32 v129, 31, v128
	v_lshlrev_b64 v[128:129], 12, v[128:129]
	v_lshl_add_u64 v[128:129], s[38:39], 0, v[128:129]
	v_lshl_add_u64 v[128:129], v[128:129], 0, v[168:169]
	v_pk_mul_f32 v[130:131], v[122:123], v[106:107]
	v_pk_mul_f32 v[122:123], v[120:121], v[104:105]
	v_cvt_pk_bf16_f32 v120, v124, v125
	v_cvt_pk_bf16_f32 v121, v126, v127
	v_pk_mul_f32 v[94:95], v[94:95], v[110:111]
	v_cvt_pk_bf16_f32 v122, v122, v123
	v_cvt_pk_bf16_f32 v123, v130, v131
	global_store_dwordx4 v[128:129], v[120:123], off
	v_pk_mul_f32 v[92:93], v[92:93], v[108:109]
	v_pk_mul_f32 v[84:85], v[84:85], v[100:101]
	v_pk_mul_f32 v[120:121], v[114:115], v[98:99]
	v_pk_mul_f32 v[114:115], v[112:113], v[96:97]
	v_cvt_pk_bf16_f32 v112, v116, v117
	v_cvt_pk_bf16_f32 v113, v118, v119
	v_pk_mul_f32 v[86:87], v[86:87], v[102:103]
	v_cvt_pk_bf16_f32 v114, v114, v115
	v_cvt_pk_bf16_f32 v115, v120, v121
	global_store_dwordx4 v[128:129], v[112:115], off offset:256
	v_pk_mul_f32 v[78:79], v[78:79], v[110:111]
	v_pk_mul_f32 v[76:77], v[76:77], v[108:109]
	v_or_b32_e32 v112, 32, v170
	v_ashrrev_i32_e32 v113, 31, v112
	v_lshlrev_b64 v[112:113], 12, v[112:113]
	v_lshl_add_u64 v[112:113], s[38:39], 0, v[112:113]
	v_lshl_add_u64 v[112:113], v[112:113], 0, v[168:169]
	v_pk_mul_f32 v[114:115], v[90:91], v[106:107]
	v_pk_mul_f32 v[90:91], v[88:89], v[104:105]
	v_cvt_pk_bf16_f32 v88, v92, v93
	v_cvt_pk_bf16_f32 v89, v94, v95
	v_pk_mul_f32 v[70:71], v[70:71], v[102:103]
	v_cvt_pk_bf16_f32 v90, v90, v91
	v_cvt_pk_bf16_f32 v91, v114, v115
	global_store_dwordx4 v[112:113], v[88:91], off
	v_pk_mul_f32 v[68:69], v[68:69], v[100:101]
	v_pk_mul_f32 v[60:61], v[60:61], v[108:109]
	v_pk_mul_f32 v[88:89], v[82:83], v[98:99]
	v_pk_mul_f32 v[82:83], v[80:81], v[96:97]
	v_cvt_pk_bf16_f32 v80, v84, v85
	v_cvt_pk_bf16_f32 v81, v86, v87
	v_pk_mul_f32 v[62:63], v[62:63], v[110:111]
	v_cvt_pk_bf16_f32 v82, v82, v83
	v_cvt_pk_bf16_f32 v83, v88, v89
	global_store_dwordx4 v[112:113], v[80:83], off offset:256
	v_pk_mul_f32 v[54:55], v[54:55], v[102:103]
	v_pk_mul_f32 v[52:53], v[52:53], v[100:101]
	v_or_b32_e32 v80, 48, v170
	v_ashrrev_i32_e32 v81, 31, v80
	v_lshlrev_b64 v[80:81], 12, v[80:81]
	v_lshl_add_u64 v[80:81], s[38:39], 0, v[80:81]
	v_lshl_add_u64 v[80:81], v[80:81], 0, v[168:169]
	v_pk_mul_f32 v[82:83], v[74:75], v[106:107]
	v_pk_mul_f32 v[74:75], v[72:73], v[104:105]
	v_cvt_pk_bf16_f32 v72, v76, v77
	v_cvt_pk_bf16_f32 v73, v78, v79
	v_pk_mul_f32 v[48:49], v[48:49], v[108:109]
	v_cvt_pk_bf16_f32 v74, v74, v75
	v_cvt_pk_bf16_f32 v75, v82, v83
	global_store_dwordx4 v[80:81], v[72:75], off
	v_pk_mul_f32 v[38:39], v[38:39], v[102:103]
	v_pk_mul_f32 v[36:37], v[36:37], v[100:101]
	v_pk_mul_f32 v[72:73], v[66:67], v[98:99]
	v_pk_mul_f32 v[66:67], v[64:65], v[96:97]
	v_cvt_pk_bf16_f32 v64, v68, v69
	v_cvt_pk_bf16_f32 v65, v70, v71
	v_pk_mul_f32 v[32:33], v[32:33], v[108:109]
	v_cvt_pk_bf16_f32 v66, v66, v67
	v_cvt_pk_bf16_f32 v67, v72, v73
	global_store_dwordx4 v[80:81], v[64:67], off offset:256
	v_pk_mul_f32 v[22:23], v[22:23], v[102:103]
	v_pk_mul_f32 v[20:21], v[20:21], v[100:101]
	v_lshl_add_u64 v[64:65], v[166:167], 0, s[10:11]
	s_mov_b32 s10, 0x80000
	v_pk_mul_f32 v[66:67], v[58:59], v[106:107]
	v_pk_mul_f32 v[58:59], v[56:57], v[104:105]
	v_cvt_pk_bf16_f32 v56, v60, v61
	v_add_co_u32_e32 v60, vcc, s10, v166
	v_cvt_pk_bf16_f32 v57, v62, v63
	v_cvt_pk_bf16_f32 v58, v58, v59
	v_cvt_pk_bf16_f32 v59, v66, v67
	s_mov_b64 s[10:11], 0x90000
	s_nop 0
	v_addc_co_u32_e32 v61, vcc, 0, v167, vcc
	global_store_dwordx4 v[60:61], v[56:59], off
	v_pk_mul_f32 v[16:17], v[16:17], v[108:109]
	v_pk_mul_f32 v[6:7], v[6:7], v[102:103]
	v_pk_mul_f32 v[56:57], v[46:47], v[98:99]
	v_pk_mul_f32 v[46:47], v[44:45], v[96:97]
	v_cvt_pk_bf16_f32 v44, v52, v53
	v_cvt_pk_bf16_f32 v45, v54, v55
	v_pk_mul_f32 v[4:5], v[4:5], v[100:101]
	v_cvt_pk_bf16_f32 v46, v46, v47
	v_cvt_pk_bf16_f32 v47, v56, v57
	global_store_dwordx4 v[64:65], v[44:47], off offset:256
	s_nop 1
	v_lshl_add_u64 v[44:45], v[166:167], 0, s[10:11]
	v_pk_mul_f32 v[46:47], v[50:51], v[110:111]
	s_mov_b32 s10, 0x90000
	v_pk_mul_f32 v[50:51], v[42:43], v[106:107]
	v_pk_mul_f32 v[42:43], v[40:41], v[104:105]
	v_cvt_pk_bf16_f32 v40, v48, v49
	v_cvt_pk_bf16_f32 v41, v46, v47
	v_add_co_u32_e32 v46, vcc, s10, v166
	v_cvt_pk_bf16_f32 v42, v42, v43
	v_cvt_pk_bf16_f32 v43, v50, v51
	s_mov_b64 s[10:11], 0xa0000
	s_nop 0
	v_addc_co_u32_e32 v47, vcc, 0, v167, vcc
	global_store_dwordx4 v[46:47], v[40:43], off
	s_nop 1
	v_pk_mul_f32 v[40:41], v[30:31], v[98:99]
	v_pk_mul_f32 v[30:31], v[28:29], v[96:97]
	v_cvt_pk_bf16_f32 v28, v36, v37
	v_cvt_pk_bf16_f32 v29, v38, v39
	s_nop 0
	v_cvt_pk_bf16_f32 v30, v30, v31
	v_cvt_pk_bf16_f32 v31, v40, v41
	global_store_dwordx4 v[44:45], v[28:31], off offset:256
	s_nop 1
	v_lshl_add_u64 v[28:29], v[166:167], 0, s[10:11]
	v_pk_mul_f32 v[30:31], v[34:35], v[110:111]
	s_mov_b32 s10, 0xa0000
	v_pk_mul_f32 v[34:35], v[26:27], v[106:107]
	v_pk_mul_f32 v[26:27], v[24:25], v[104:105]
	v_cvt_pk_bf16_f32 v24, v32, v33
	v_cvt_pk_bf16_f32 v25, v30, v31
	v_add_co_u32_e32 v30, vcc, s10, v166
	v_cvt_pk_bf16_f32 v26, v26, v27
	v_cvt_pk_bf16_f32 v27, v34, v35
	s_mov_b64 s[10:11], 0xb0000
	s_nop 0
	v_addc_co_u32_e32 v31, vcc, 0, v167, vcc
	global_store_dwordx4 v[30:31], v[24:27], off
	s_nop 1
	v_pk_mul_f32 v[24:25], v[14:15], v[98:99]
	v_pk_mul_f32 v[14:15], v[12:13], v[96:97]
	v_cvt_pk_bf16_f32 v12, v20, v21
	v_cvt_pk_bf16_f32 v13, v22, v23
	s_nop 0
	v_cvt_pk_bf16_f32 v14, v14, v15
	v_cvt_pk_bf16_f32 v15, v24, v25
	global_store_dwordx4 v[28:29], v[12:15], off offset:256
	s_nop 1
	v_lshl_add_u64 v[12:13], v[166:167], 0, s[10:11]
	v_pk_mul_f32 v[14:15], v[18:19], v[110:111]
	s_mov_b32 s10, 0xb0000
	v_pk_mul_f32 v[18:19], v[10:11], v[106:107]
	v_pk_mul_f32 v[10:11], v[8:9], v[104:105]
	v_cvt_pk_bf16_f32 v8, v16, v17
	v_cvt_pk_bf16_f32 v9, v14, v15
	v_add_co_u32_e32 v14, vcc, s10, v166
	v_cvt_pk_bf16_f32 v10, v10, v11
	v_cvt_pk_bf16_f32 v11, v18, v19
	s_nop 1
	v_addc_co_u32_e32 v15, vcc, 0, v167, vcc
	global_store_dwordx4 v[14:15], v[8:11], off
	s_andn2_b64 vcc, exec, s[40:41]
	s_nop 0
	v_pk_mul_f32 v[8:9], v[2:3], v[98:99]
	v_pk_mul_f32 v[2:3], v[0:1], v[96:97]
	v_cvt_pk_bf16_f32 v0, v4, v5
	v_cvt_pk_bf16_f32 v1, v6, v7
	s_nop 0
	v_cvt_pk_bf16_f32 v2, v2, v3
	v_cvt_pk_bf16_f32 v3, v8, v9
	global_store_dwordx4 v[12:13], v[0:3], off offset:256
	s_cbranch_vccnz .LBB0_705
	s_andn2_b64 vcc, exec, s[42:43]
	s_cbranch_vccnz .LBB0_704
	s_barrier
	s_branch .LBB0_704

.LBB0_856:
	s_cmp_lt_i32 s70, 13
	s_cselect_b64 s[0:1], -1, 0
	s_cmp_gt_i32 s71, 12
	s_cselect_b64 s[2:3], -1, 0
	s_and_b64 s[0:1], s[0:1], s[2:3]
	s_and_b64 vcc, exec, s[0:1]
	s_cbranch_vccz .LBB0_862
	v_readlane_b32 s0, v243, 62
	v_ashrrev_i32_e32 v0, 6, v175
	s_movk_i32 s16, 0x4000
	v_add_u32_e32 v96, s0, v0
	v_cmp_gt_i32_e32 vcc, s16, v96
	s_and_saveexec_b64 s[0:1], vcc
	v_readlane_b32 s20, v242, 20
	v_readlane_b32 s22, v242, 22
	v_readlane_b32 s21, v242, 21
	v_readlane_b32 s23, v242, 23
	s_cbranch_execz .LBB0_862
	v_lshlrev_b32_e32 v0, 3, v175
	s_add_u32 s10, s68, 0x15e9c000
	s_waitcnt vmcnt(0)
	v_and_b32_e32 v36, 0x1f8, v0
	s_addc_u32 s11, s69, 0
	v_lshlrev_b32_e32 v28, 2, v36
	global_load_dwordx4 v[8:11], v28, s[10:11]
	global_load_dwordx4 v[12:15], v28, s[10:11] offset:16
	v_readlane_b32 s0, v242, 30
	v_readlane_b32 s1, v242, 31
	s_load_dwordx4 s[12:15], s[0:1], 0xc0
	v_or_b32_e32 v24, 0x800, v28
	global_load_dwordx4 v[16:19], v24, s[10:11] offset:16
	global_load_dwordx4 v[20:23], v24, s[10:11]
	s_waitcnt lgkmcnt(0)
	global_load_dwordx4 v[0:3], v28, s[12:13] offset:16
	global_load_dwordx4 v[4:7], v28, s[12:13]
	v_ashrrev_i32_e32 v97, 31, v96
	v_lshlrev_b32_e32 v36, 1, v36
	v_mov_b32_e32 v134, 0x260
	s_waitcnt vmcnt(5)
	v_div_scale_f32 v24, s[0:1], v8, v8, 1.0
	v_div_scale_f32 v26, s[0:1], v9, v9, 1.0
	v_rcp_f32_e32 v39, v24
	v_div_scale_f32 v29, s[2:3], v10, v10, 1.0
	v_rcp_f32_e32 v40, v26
	v_div_scale_f32 v31, s[4:5], v11, v11, 1.0
	v_rcp_f32_e32 v41, v29
	s_waitcnt vmcnt(4)
	v_div_scale_f32 v33, s[6:7], v12, v12, 1.0
	v_rcp_f32_e32 v42, v31
	v_div_scale_f32 v35, s[8:9], v13, v13, 1.0
	v_rcp_f32_e32 v43, v33
	v_fma_f32 v46, -v24, v39, 1.0
	v_div_scale_f32 v25, vcc, 1.0, v8, 1.0
	v_rcp_f32_e32 v44, v35
	v_fma_f32 v47, -v26, v40, 1.0
	v_fmac_f32_e32 v39, v46, v39
	v_div_scale_f32 v27, s[0:1], 1.0, v9, 1.0
	v_fma_f32 v48, -v29, v41, 1.0
	v_fmac_f32_e32 v40, v47, v40
	v_mul_f32_e32 v46, v25, v39
	v_div_scale_f32 v30, s[2:3], 1.0, v10, 1.0
	v_fma_f32 v49, -v31, v42, 1.0
	v_fmac_f32_e32 v41, v48, v41
	v_mul_f32_e32 v47, v27, v40
	v_fma_f32 v53, -v24, v46, v25
	v_div_scale_f32 v32, s[4:5], 1.0, v11, 1.0
	v_fma_f32 v50, -v33, v43, 1.0
	v_fmac_f32_e32 v42, v49, v42
	v_mul_f32_e32 v48, v30, v41
	v_fma_f32 v54, -v26, v47, v27
	v_fmac_f32_e32 v46, v53, v39
	v_div_scale_f32 v34, s[6:7], 1.0, v12, 1.0
	v_fma_f32 v51, -v35, v44, 1.0
	v_fmac_f32_e32 v43, v50, v43
	v_mul_f32_e32 v49, v32, v42
	v_fma_f32 v55, -v29, v48, v30
	v_fmac_f32_e32 v47, v54, v40
	v_fma_f32 v24, -v24, v46, v25
	v_div_scale_f32 v37, s[8:9], 1.0, v13, 1.0
	v_div_scale_f32 v38, s[18:19], v14, v14, 1.0
	v_fmac_f32_e32 v44, v51, v44
	v_mul_f32_e32 v50, v34, v43
	v_fma_f32 v56, -v31, v49, v32
	v_fmac_f32_e32 v48, v55, v41
	v_fma_f32 v25, -v26, v47, v27
	v_div_fmas_f32 v24, v24, v39, v46
	s_mov_b64 vcc, s[0:1]
	v_rcp_f32_e32 v45, v38
	v_mul_f32_e32 v51, v37, v44
	v_fma_f32 v57, -v33, v50, v34
	v_fmac_f32_e32 v49, v56, v42
	v_fma_f32 v26, -v29, v48, v30
	v_div_fixup_f32 v98, v24, v8, 1.0
	v_div_fmas_f32 v8, v25, v40, v47
	s_mov_b64 vcc, s[2:3]
	v_fma_f32 v58, -v35, v51, v37
	v_fmac_f32_e32 v50, v57, v43
	v_fma_f32 v27, -v31, v49, v32
	v_div_fixup_f32 v99, v8, v9, 1.0
	v_div_fmas_f32 v8, v26, v41, v48
	s_mov_b64 vcc, s[4:5]
	v_fmac_f32_e32 v51, v58, v44
	v_fma_f32 v29, -v33, v50, v34
	v_div_fixup_f32 v100, v8, v10, 1.0
	v_div_fmas_f32 v8, v27, v42, v49
	s_mov_b64 vcc, s[6:7]
	v_fma_f32 v30, -v35, v51, v37
	v_div_fixup_f32 v101, v8, v11, 1.0
	v_div_fmas_f32 v8, v29, v43, v50
	s_mov_b64 vcc, s[8:9]
	v_fma_f32 v52, -v38, v45, 1.0
	v_div_fixup_f32 v102, v8, v12, 1.0
	v_div_fmas_f32 v8, v30, v44, v51
	v_div_fixup_f32 v103, v8, v13, 1.0
	v_fmac_f32_e32 v45, v52, v45
	v_div_scale_f32 v8, vcc, 1.0, v14, 1.0
	v_mul_f32_e32 v9, v8, v45
	v_fma_f32 v10, -v38, v9, v8
	v_fmac_f32_e32 v9, v10, v45
	v_div_scale_f32 v10, s[0:1], v15, v15, 1.0
	v_rcp_f32_e32 v11, v10
	v_fma_f32 v8, -v38, v9, v8
	v_div_fmas_f32 v8, v8, v45, v9
	v_div_fixup_f32 v104, v8, v14, 1.0
	v_fma_f32 v8, -v10, v11, 1.0
	s_waitcnt vmcnt(2)
	v_div_scale_f32 v24, s[0:1], v20, v20, 1.0
	v_fmac_f32_e32 v11, v8, v11
	v_div_scale_f32 v8, vcc, 1.0, v15, 1.0
	v_rcp_f32_e32 v25, v24
	v_mul_f32_e32 v9, v8, v11
	v_fma_f32 v12, -v10, v9, v8
	v_fmac_f32_e32 v9, v12, v11
	v_fma_f32 v8, -v10, v9, v8
	v_fma_f32 v26, -v24, v25, 1.0
	v_div_fmas_f32 v8, v8, v11, v9
	v_fmac_f32_e32 v25, v26, v25
	v_div_scale_f32 v26, vcc, 1.0, v20, 1.0
	v_mul_f32_e32 v27, v26, v25
	v_fma_f32 v29, -v24, v27, v26
	v_fmac_f32_e32 v27, v29, v25
	v_fma_f32 v24, -v24, v27, v26
	v_div_scale_f32 v26, s[0:1], v21, v21, 1.0
	v_rcp_f32_e32 v29, v26
	v_div_fmas_f32 v24, v24, v25, v27
	v_div_fixup_f32 v106, v24, v20, 1.0
	v_div_fixup_f32 v105, v8, v15, 1.0
	v_fma_f32 v20, -v26, v29, 1.0
	v_fmac_f32_e32 v29, v20, v29
	v_div_scale_f32 v20, vcc, 1.0, v21, 1.0
	v_mul_f32_e32 v24, v20, v29
	v_fma_f32 v25, -v26, v24, v20
	v_fmac_f32_e32 v24, v25, v29
	v_fma_f32 v20, -v26, v24, v20
	v_div_fmas_f32 v20, v20, v29, v24
	v_or_b32_e32 v29, 0x1000, v28
	global_load_dwordx4 v[8:11], v28, s[12:13] offset:2064
	global_load_dwordx4 v[12:15], v28, s[12:13] offset:2048
	global_load_dwordx4 v[24:27], v29, s[10:11] offset:16
	global_load_dwordx4 v[38:41], v29, s[10:11]
	v_div_scale_f32 v30, s[0:1], v22, v22, 1.0
	v_rcp_f32_e32 v31, v30
	v_div_fixup_f32 v107, v20, v21, 1.0
	s_mov_b64 s[2:3], 0x16374d00
	s_lshl_b64 s[4:5], s[20:21], 13
	v_fma_f32 v20, -v30, v31, 1.0
	v_fmac_f32_e32 v31, v20, v31
	v_div_scale_f32 v20, vcc, 1.0, v22, 1.0
	v_mul_f32_e32 v21, v20, v31
	v_fma_f32 v32, -v30, v21, v20
	v_fmac_f32_e32 v21, v32, v31
	v_fma_f32 v20, -v30, v21, v20
	v_div_scale_f32 v30, s[0:1], v23, v23, 1.0
	v_rcp_f32_e32 v32, v30
	v_div_fmas_f32 v20, v20, v31, v21
	v_div_fixup_f32 v108, v20, v22, 1.0
	s_mov_b64 s[6:7], 0
	v_fma_f32 v20, -v30, v32, 1.0
	v_fmac_f32_e32 v32, v20, v32
	v_div_scale_f32 v20, vcc, 1.0, v23, 1.0
	v_mul_f32_e32 v21, v20, v32
	v_fma_f32 v22, -v30, v21, v20
	v_fmac_f32_e32 v21, v22, v32
	v_div_scale_f32 v22, s[0:1], v16, v16, 1.0
	v_fma_f32 v20, -v30, v21, v20
	v_rcp_f32_e32 v30, v22
	v_div_fmas_f32 v20, v20, v32, v21
	v_div_fixup_f32 v109, v20, v23, 1.0
	s_movk_i32 s8, 0x3fff
	v_fma_f32 v20, -v22, v30, 1.0
	v_fmac_f32_e32 v30, v20, v30
	v_div_scale_f32 v20, vcc, 1.0, v16, 1.0
	v_mul_f32_e32 v21, v20, v30
	v_fma_f32 v23, -v22, v21, v20
	v_fmac_f32_e32 v21, v23, v30
	v_fma_f32 v20, -v22, v21, v20
	v_div_scale_f32 v22, s[0:1], v17, v17, 1.0
	v_rcp_f32_e32 v23, v22
	v_div_fmas_f32 v20, v20, v30, v21
	v_div_fixup_f32 v110, v20, v16, 1.0
	s_mov_b32 s9, 0xf800000
	v_fma_f32 v16, -v22, v23, 1.0
	v_fmac_f32_e32 v23, v16, v23
	v_div_scale_f32 v16, vcc, 1.0, v17, 1.0
	v_mul_f32_e32 v20, v16, v23
	v_fma_f32 v21, -v22, v20, v16
	v_fmac_f32_e32 v20, v21, v23
	v_div_scale_f32 v21, s[0:1], v18, v18, 1.0
	v_fma_f32 v16, -v22, v20, v16
	v_rcp_f32_e32 v22, v21
	v_div_fmas_f32 v16, v16, v23, v20
	v_div_fixup_f32 v111, v16, v17, 1.0
	v_fma_f32 v16, -v21, v22, 1.0
	v_fmac_f32_e32 v22, v16, v22
	v_div_scale_f32 v16, vcc, 1.0, v18, 1.0
	v_mul_f32_e32 v17, v16, v22
	v_fma_f32 v20, -v21, v17, v16
	v_fmac_f32_e32 v17, v20, v22
	v_div_scale_f32 v20, s[0:1], v19, v19, 1.0
	v_fma_f32 v16, -v21, v17, v16
	v_rcp_f32_e32 v21, v20
	v_div_fmas_f32 v16, v16, v22, v17
	v_div_fixup_f32 v112, v16, v18, 1.0
	v_fma_f32 v16, -v20, v21, 1.0
	v_fmac_f32_e32 v21, v16, v21
	v_div_scale_f32 v16, vcc, 1.0, v19, 1.0
	v_mul_f32_e32 v17, v16, v21
	s_waitcnt vmcnt(0)
	v_div_scale_f32 v30, s[0:1], v38, v38, 1.0
	v_fma_f32 v18, -v20, v17, v16
	v_rcp_f32_e32 v31, v30
	v_fmac_f32_e32 v17, v18, v21
	v_fma_f32 v16, -v20, v17, v16
	v_div_fmas_f32 v16, v16, v21, v17
	v_div_fixup_f32 v113, v16, v19, 1.0
	global_load_dwordx4 v[16:19], v29, s[12:13] offset:16
	global_load_dwordx4 v[20:23], v29, s[12:13]
	v_fma_f32 v29, -v30, v31, 1.0
	v_fmac_f32_e32 v31, v29, v31
	v_div_scale_f32 v29, vcc, 1.0, v38, 1.0
	v_mul_f32_e32 v32, v29, v31
	v_fma_f32 v33, -v30, v32, v29
	v_fmac_f32_e32 v32, v33, v31
	v_fma_f32 v29, -v30, v32, v29
	v_div_scale_f32 v30, s[0:1], v39, v39, 1.0
	v_rcp_f32_e32 v33, v30
	v_div_fmas_f32 v29, v29, v31, v32
	v_div_fixup_f32 v114, v29, v38, 1.0
	v_or_b32_e32 v38, 0x1800, v28
	v_fma_f32 v29, -v30, v33, 1.0
	v_fmac_f32_e32 v33, v29, v33
	v_div_scale_f32 v29, vcc, 1.0, v39, 1.0
	v_mul_f32_e32 v31, v29, v33
	v_fma_f32 v32, -v30, v31, v29
	v_fmac_f32_e32 v31, v32, v33
	v_fma_f32 v29, -v30, v31, v29
	v_div_fmas_f32 v29, v29, v33, v31
	global_load_dwordx4 v[32:35], v38, s[10:11] offset:16
	global_load_dwordx4 v[42:45], v38, s[10:11]
	v_div_scale_f32 v30, s[0:1], v40, v40, 1.0
	v_rcp_f32_e32 v37, v30
	v_div_fixup_f32 v115, v29, v39, 1.0
	v_div_scale_f32 v28, vcc, 1.0, v40, 1.0
	v_fma_f32 v29, -v30, v37, 1.0
	v_fmac_f32_e32 v37, v29, v37
	v_mul_f32_e32 v29, v28, v37
	v_fma_f32 v31, -v30, v29, v28
	v_fmac_f32_e32 v29, v31, v37
	v_fma_f32 v28, -v30, v29, v28
	v_div_scale_f32 v30, s[0:1], v41, v41, 1.0
	v_rcp_f32_e32 v31, v30
	v_div_fmas_f32 v28, v28, v37, v29
	v_div_fixup_f32 v116, v28, v40, 1.0
	v_fma_f32 v28, -v30, v31, 1.0
	v_fmac_f32_e32 v31, v28, v31
	v_div_scale_f32 v28, vcc, 1.0, v41, 1.0
	v_mul_f32_e32 v29, v28, v31
	v_fma_f32 v37, -v30, v29, v28
	v_fmac_f32_e32 v29, v37, v31
	v_fma_f32 v28, -v30, v29, v28
	v_div_scale_f32 v30, s[0:1], v24, v24, 1.0
	v_rcp_f32_e32 v37, v30
	v_div_fmas_f32 v28, v28, v31, v29
	v_div_fixup_f32 v117, v28, v41, 1.0
	v_fma_f32 v28, -v30, v37, 1.0
	v_fmac_f32_e32 v37, v28, v37
	v_div_scale_f32 v28, vcc, 1.0, v24, 1.0
	v_mul_f32_e32 v29, v28, v37
	v_fma_f32 v31, -v30, v29, v28
	v_fmac_f32_e32 v29, v31, v37
	v_fma_f32 v28, -v30, v29, v28
	v_div_scale_f32 v30, s[0:1], v25, v25, 1.0
	v_rcp_f32_e32 v31, v30
	v_div_fmas_f32 v28, v28, v37, v29
	v_div_fixup_f32 v118, v28, v24, 1.0
	v_fma_f32 v24, -v30, v31, 1.0
	v_fmac_f32_e32 v31, v24, v31
	v_div_scale_f32 v24, vcc, 1.0, v25, 1.0
	v_mul_f32_e32 v28, v24, v31
	v_fma_f32 v29, -v30, v28, v24
	v_fmac_f32_e32 v28, v29, v31
	v_div_scale_f32 v29, s[0:1], v26, v26, 1.0
	v_fma_f32 v24, -v30, v28, v24
	v_rcp_f32_e32 v30, v29
	v_div_fmas_f32 v24, v24, v31, v28
	v_div_fixup_f32 v119, v24, v25, 1.0
	v_fma_f32 v24, -v29, v30, 1.0
	v_fmac_f32_e32 v30, v24, v30
	v_div_scale_f32 v24, vcc, 1.0, v26, 1.0
	v_mul_f32_e32 v25, v24, v30
	v_fma_f32 v28, -v29, v25, v24
	v_fmac_f32_e32 v25, v28, v30
	v_div_scale_f32 v28, s[0:1], v27, v27, 1.0
	v_fma_f32 v24, -v29, v25, v24
	v_rcp_f32_e32 v29, v28
	v_div_fmas_f32 v24, v24, v30, v25
	v_div_fixup_f32 v120, v24, v26, 1.0
	v_fma_f32 v24, -v28, v29, 1.0
	v_fmac_f32_e32 v29, v24, v29
	v_div_scale_f32 v24, vcc, 1.0, v27, 1.0
	v_mul_f32_e32 v25, v24, v29
	s_waitcnt vmcnt(0)
	v_div_scale_f32 v37, s[0:1], v42, v42, 1.0
	v_fma_f32 v26, -v28, v25, v24
	v_rcp_f32_e32 v39, v37
	v_fmac_f32_e32 v25, v26, v29
	v_fma_f32 v24, -v28, v25, v24
	v_div_fmas_f32 v24, v24, v29, v25
	v_div_fixup_f32 v121, v24, v27, 1.0
	global_load_dwordx4 v[24:27], v38, s[12:13] offset:16
	global_load_dwordx4 v[28:31], v38, s[12:13]
	v_fma_f32 v38, -v37, v39, 1.0
	v_fmac_f32_e32 v39, v38, v39
	v_div_scale_f32 v38, vcc, 1.0, v42, 1.0
	v_mul_f32_e32 v40, v38, v39
	v_fma_f32 v41, -v37, v40, v38
	v_fmac_f32_e32 v40, v41, v39
	v_fma_f32 v37, -v37, v40, v38
	v_div_scale_f32 v38, s[0:1], v43, v43, 1.0
	v_rcp_f32_e32 v41, v38
	v_div_fmas_f32 v37, v37, v39, v40
	v_div_fixup_f32 v122, v37, v42, 1.0
	v_div_scale_f32 v46, s[0:1], v45, v45, 1.0
	v_fma_f32 v37, -v38, v41, 1.0
	v_fmac_f32_e32 v41, v37, v41
	v_div_scale_f32 v37, vcc, 1.0, v43, 1.0
	v_mul_f32_e32 v39, v37, v41
	v_fma_f32 v40, -v38, v39, v37
	v_fmac_f32_e32 v39, v40, v41
	v_fma_f32 v37, -v38, v39, v37
	v_div_scale_f32 v38, s[0:1], v44, v44, 1.0
	v_rcp_f32_e32 v40, v38
	v_div_fmas_f32 v37, v37, v41, v39
	v_div_fixup_f32 v123, v37, v43, 1.0
	v_rcp_f32_e32 v47, v46
	v_fma_f32 v37, -v38, v40, 1.0
	v_fmac_f32_e32 v40, v37, v40
	v_div_scale_f32 v37, vcc, 1.0, v44, 1.0
	v_mul_f32_e32 v39, v37, v40
	v_fma_f32 v41, -v38, v39, v37
	v_fmac_f32_e32 v39, v41, v40
	v_fma_f32 v37, -v38, v39, v37
	v_div_fmas_f32 v37, v37, v40, v39
	v_div_fixup_f32 v124, v37, v44, 1.0
	v_fma_f32 v37, -v46, v47, 1.0
	v_fmac_f32_e32 v47, v37, v47
	v_div_scale_f32 v44, vcc, 1.0, v45, 1.0
	v_mul_f32_e32 v48, v44, v47
	v_fma_f32 v37, -v46, v48, v44
	v_lshlrev_b64 v[38:39], 12, v[96:97]
	v_fmac_f32_e32 v48, v37, v47
	v_lshl_add_u64 v[38:39], s[68:69], 0, v[38:39]
	v_mov_b32_e32 v37, 0
	v_lshl_add_u64 v[36:37], v[38:39], 0, v[36:37]
	s_mov_b64 s[0:1], 0x3900000
	v_lshl_add_u64 v[38:39], v[36:37], 0, s[0:1]
	s_mov_b32 s0, 0x3900000
	v_add_co_u32_e64 v40, s[0:1], s0, v36
	v_lshl_add_u64 v[42:43], v[36:37], 0, s[2:3]
	s_nop 0
	v_addc_co_u32_e64 v41, s[0:1], 0, v37, s[0:1]
	s_mov_b32 s0, 0x16374000
	s_nop 0
	v_add_co_u32_e64 v36, s[0:1], s0, v36
	s_nop 1
	v_addc_co_u32_e64 v37, s[0:1], 0, v37, s[0:1]
	global_load_dwordx4 v[84:87], v[38:39], off offset:1024 nt
	global_load_dwordx4 v[76:79], v[38:39], off offset:2048 nt
	global_load_dwordx4 v[92:95], v[40:41], off nt
	global_load_dwordx4 v[68:71], v[38:39], off offset:3072 nt
	v_div_scale_f32 v37, s[0:1], v32, v32, 1.0
	v_rcp_f32_e32 v38, v37
	v_fma_f32 v36, -v46, v48, v44
	v_div_fmas_f32 v36, v36, v47, v48
	v_div_fixup_f32 v125, v36, v45, 1.0
	v_fma_f32 v36, -v37, v38, 1.0
	v_fmac_f32_e32 v38, v36, v38
	v_div_scale_f32 v36, vcc, 1.0, v32, 1.0
	v_mul_f32_e32 v39, v36, v38
	v_fma_f32 v40, -v37, v39, v36
	v_fmac_f32_e32 v39, v40, v38
	v_fma_f32 v36, -v37, v39, v36
	v_div_scale_f32 v37, s[0:1], v33, v33, 1.0
	v_rcp_f32_e32 v40, v37
	v_div_fmas_f32 v36, v36, v38, v39
	v_div_fixup_f32 v126, v36, v32, 1.0
	v_fma_f32 v32, -v37, v40, 1.0
	v_fmac_f32_e32 v40, v32, v40
	v_div_scale_f32 v32, vcc, 1.0, v33, 1.0
	v_mul_f32_e32 v36, v32, v40
	v_fma_f32 v38, -v37, v36, v32
	v_fmac_f32_e32 v36, v38, v40
	v_fma_f32 v32, -v37, v36, v32
	v_div_scale_f32 v37, s[0:1], v34, v34, 1.0
	v_rcp_f32_e32 v38, v37
	v_div_fmas_f32 v32, v32, v40, v36
	v_div_fixup_f32 v127, v32, v33, 1.0
	v_fma_f32 v32, -v37, v38, 1.0
	v_fmac_f32_e32 v38, v32, v38
	v_div_scale_f32 v32, vcc, 1.0, v34, 1.0
	v_mul_f32_e32 v33, v32, v38
	v_fma_f32 v36, -v37, v33, v32
	v_fmac_f32_e32 v33, v36, v38
	v_div_scale_f32 v36, s[0:1], v35, v35, 1.0
	v_fma_f32 v32, -v37, v33, v32
	v_rcp_f32_e32 v37, v36
	v_div_fmas_f32 v32, v32, v38, v33
	v_div_fixup_f32 v128, v32, v34, 1.0
	s_mov_b64 s[0:1], 0x1000
	v_fma_f32 v32, -v36, v37, 1.0
	v_fmac_f32_e32 v37, v32, v37
	v_div_scale_f32 v32, vcc, 1.0, v35, 1.0
	v_mul_f32_e32 v33, v32, v37
	v_fma_f32 v34, -v36, v33, v32
	v_fmac_f32_e32 v33, v34, v37
	v_fma_f32 v32, -v36, v33, v32
	v_div_fmas_f32 v32, v32, v37, v33
	v_div_fixup_f32 v129, v32, v35, 1.0
	v_lshlrev_b64 v[32:33], 13, v[96:97]
	v_and_b32_e32 v34, 63, v175
	v_lshl_or_b32 v32, v34, 5, v32
	v_lshl_add_u64 v[32:33], s[14:15], 0, v[32:33]
	v_lshl_add_u64 v[130:131], v[32:33], 0, s[0:1]
	v_add_u32_e32 v32, s20, v96
	v_ashrrev_i32_e32 v33, 31, v32
	v_lshlrev_b64 v[32:33], 12, v[32:33]
	v_lshl_or_b32 v32, v34, 4, v32
	v_lshl_add_u64 v[32:33], s[68:69], 0, v[32:33]
	v_lshl_add_u64 v[132:133], v[32:33], 0, s[2:3]
	v_mov_b32_e32 v97, 0x358637bd
	v_mov_b32_e32 v48, 0
	v_mov_b32_e32 v49, 0
	v_mov_b32_e32 v50, 0
	v_mov_b32_e32 v51, 0
	v_mov_b32_e32 v52, 0
	v_mov_b32_e32 v53, 0
	v_mov_b32_e32 v54, 0
	v_mov_b32_e32 v55, 0
	v_mov_b32_e32 v56, 0
	v_mov_b32_e32 v57, 0
	v_mov_b32_e32 v58, 0
	v_mov_b32_e32 v59, 0
	v_mov_b32_e32 v60, 0
	v_mov_b32_e32 v61, 0
	v_mov_b32_e32 v62, 0
	v_mov_b32_e32 v63, 0
	v_mov_b32_e32 v64, 0
	v_mov_b32_e32 v65, 0
	v_mov_b32_e32 v66, 0
	v_mov_b32_e32 v67, 0
	v_mov_b32_e32 v72, 0
	v_mov_b32_e32 v73, 0
	v_mov_b32_e32 v74, 0
	v_mov_b32_e32 v75, 0
	v_mov_b32_e32 v80, 0
	v_mov_b32_e32 v81, 0
	v_mov_b32_e32 v82, 0
	v_mov_b32_e32 v83, 0
	v_mov_b32_e32 v88, 0
	v_mov_b32_e32 v89, 0
	v_mov_b32_e32 v90, 0
	v_mov_b32_e32 v91, 0
	s_branch .LBB0_860

.LBB0_860:
	v_add_u32_e32 v96, s20, v96
	v_cmp_gt_i32_e32 vcc, s16, v96
	v_cmp_lt_i32_e64 s[0:1], s8, v96
	s_and_saveexec_b64 s[2:3], vcc
	s_cbranch_execz .Lfn_skip
	v_add_co_u32_e32 v44, vcc, 0xed58c000, v132
	s_nop 1
	v_addc_co_u32_e32 v45, vcc, -1, v133, vcc
	global_load_dwordx4 v[32:35], v[44:45], off offset:-3328 nt
	global_load_dwordx4 v[36:39], v[44:45], off offset:-2304 nt
	global_load_dwordx4 v[40:43], v[44:45], off offset:-1280 nt
	s_nop 0
	global_load_dwordx4 v[44:47], v[44:45], off offset:-256 nt
	s_nop 0
	s_waitcnt vmcnt(4)
	s_branch .LBB0_859

.Lfe_start:
	v_lshl_or_b32 v166, s96, 8, v174
	v_ashrrev_i32_e32 v167, 31, v166
	v_lshl_add_u64 v[100:101], v[166:167], 2, s[44:45]
	global_load_dwordx4 v[104:107], v[100:101], off offset:16
	global_load_dwordx4 v[108:111], v[100:101], off
	global_load_dwordx4 v[96:99], v[100:101], off offset:528
	s_nop 0
	global_load_dwordx4 v[100:103], v[100:101], off offset:512
	v_lshl_add_u32 v170, s92, 8, v172
	v_ashrrev_i32_e32 v171, 31, v170
	s_add_u32 s100, s68, 0x3900000
	s_addc_u32 s101, s69, 0
	v_lshlrev_b64 v[168:169], 12, v[170:171]
	v_lshl_add_u64 v[168:169], s[100:101], 0, v[168:169]
	v_lshl_add_u64 v[168:169], v[166:167], 1, v[168:169]
	s_mov_b64 s[58:59], -1
	s_add_u32 s98, s68, 0x15e9c000
	s_addc_u32 s99, s69, 0
	v_lshl_add_u64 v[234:235], v[166:167], 2, s[98:99]
	global_load_dwordx4 v[190:193], v[234:235], off
	global_load_dwordx4 v[194:197], v[234:235], off offset:16
	v_readlane_b32 s98, v242, 47
	s_nop 3
	s_cmp_eq_u32 s98, 0
	s_mov_b32 s98, 0x15e9c000
	s_cselect_b32 s98, 0x15e98000, s98
	s_add_u32 s98, s68, s98
	s_addc_u32 s99, s69, 0
	v_lshl_add_u64 v[234:235], v[166:167], 2, s[98:99]
	global_load_dwordx4 v[198:201], v[234:235], off
	global_load_dwordx4 v[202:205], v[234:235], off offset:16
	v_mov_b32_e32 v166, v168
	v_mov_b32_e32 v167, v169
	global_load_dwordx4 v[206:209], v[166:167], off
	v_add_co_u32_e32 v166, vcc, 0x10000, v168
	s_nop 1
	v_addc_co_u32_e32 v167, vcc, 0, v169, vcc
	global_load_dwordx4 v[210:213], v[166:167], off
	v_add_co_u32_e32 v166, vcc, 0x20000, v168
	s_nop 1
	v_addc_co_u32_e32 v167, vcc, 0, v169, vcc
	global_load_dwordx4 v[214:217], v[166:167], off
	v_add_co_u32_e32 v166, vcc, 0x30000, v168
	s_nop 1
	v_addc_co_u32_e32 v167, vcc, 0, v169, vcc
	global_load_dwordx4 v[218:221], v[166:167], off
	v_add_co_u32_e32 v166, vcc, 0x80000, v168
	s_nop 1
	v_addc_co_u32_e32 v167, vcc, 0, v169, vcc
	global_load_dwordx4 v[222:225], v[166:167], off
	v_add_co_u32_e32 v166, vcc, 0x90000, v168
	s_nop 1
	v_addc_co_u32_e32 v167, vcc, 0, v169, vcc
	global_load_dwordx4 v[226:229], v[166:167], off
	v_add_co_u32_e32 v166, vcc, 0xa0000, v168
	s_nop 1
	v_addc_co_u32_e32 v167, vcc, 0, v169, vcc
	global_load_dwordx4 v[230:233], v[166:167], off
	s_waitcnt vmcnt(7)
	v_rcp_f32_e32 v198, v198
	v_rcp_f32_e32 v199, v199
	v_rcp_f32_e32 v200, v200
	v_rcp_f32_e32 v201, v201
	v_rcp_f32_e32 v202, v202
	v_rcp_f32_e32 v203, v203
	v_rcp_f32_e32 v204, v204
	v_rcp_f32_e32 v205, v205
	s_waitcnt vmcnt(11)
	s_waitcnt vmcnt(6)
	v_lshlrev_b32_e32 v234, 16, v206
	v_lshlrev_b32_e32 v236, 16, v207
	v_lshlrev_b32_e32 v238, 16, v208
	v_lshlrev_b32_e32 v240, 16, v209
	v_and_b32_e32 v235, 0xffff0000, v206
	v_and_b32_e32 v237, 0xffff0000, v207
	v_and_b32_e32 v239, 0xffff0000, v208
	v_and_b32_e32 v241, 0xffff0000, v209
	v_pk_mul_f32 v[234:235], v[234:235], v[198:199]
	v_pk_mul_f32 v[236:237], v[236:237], v[200:201]
	v_pk_mul_f32 v[238:239], v[238:239], v[202:203]
	v_pk_mul_f32 v[240:241], v[240:241], v[204:205]
	v_pk_fma_f32 v[140:141], v[140:141], v[108:109], v[234:235]
	v_pk_fma_f32 v[142:143], v[142:143], v[110:111], v[236:237]
	v_pk_fma_f32 v[136:137], v[136:137], v[104:105], v[238:239]
	v_pk_fma_f32 v[138:139], v[138:139], v[106:107], v[240:241]
	v_pk_mul_f32 v[246:247], v[140:141], v[140:141]
	v_pk_mul_f32 v[234:235], v[140:141], v[190:191]
	v_pk_mul_f32 v[236:237], v[142:143], v[192:193]
	v_pk_fma_f32 v[246:247], v[142:143], v[142:143], v[246:247]
	v_pk_mul_f32 v[238:239], v[136:137], v[194:195]
	v_pk_fma_f32 v[246:247], v[136:137], v[136:137], v[246:247]
	v_pk_mul_f32 v[240:241], v[138:139], v[196:197]
	v_pk_fma_f32 v[246:247], v[138:139], v[138:139], v[246:247]
	v_cvt_pk_bf16_f32 v136, v234, v235
	v_cvt_pk_bf16_f32 v137, v236, v237
	v_cvt_pk_bf16_f32 v138, v238, v239
	v_cvt_pk_bf16_f32 v139, v240, v241
	v_add_f32_e32 v140, v246, v247
	v_mov_b32_e32 v166, v168
	v_mov_b32_e32 v167, v169
	global_store_dwordx4 v[166:167], v[136:139], off
	v_add_co_u32_e32 v166, vcc, 0xb0000, v168
	s_nop 1
	v_addc_co_u32_e32 v167, vcc, 0, v169, vcc
	global_load_dwordx4 v[206:209], v[166:167], off
	s_waitcnt vmcnt(7)
	v_lshlrev_b32_e32 v234, 16, v210
	v_lshlrev_b32_e32 v236, 16, v211
	v_lshlrev_b32_e32 v238, 16, v212
	v_lshlrev_b32_e32 v240, 16, v213
	v_and_b32_e32 v235, 0xffff0000, v210
	v_and_b32_e32 v237, 0xffff0000, v211
	v_and_b32_e32 v239, 0xffff0000, v212
	v_and_b32_e32 v241, 0xffff0000, v213
	v_pk_mul_f32 v[234:235], v[234:235], v[198:199]
	v_pk_mul_f32 v[236:237], v[236:237], v[200:201]
	v_pk_mul_f32 v[238:239], v[238:239], v[202:203]
	v_pk_mul_f32 v[240:241], v[240:241], v[204:205]
	v_pk_fma_f32 v[124:125], v[124:125], v[108:109], v[234:235]
	v_pk_fma_f32 v[126:127], v[126:127], v[110:111], v[236:237]
	v_pk_fma_f32 v[120:121], v[120:121], v[104:105], v[238:239]
	v_pk_fma_f32 v[122:123], v[122:123], v[106:107], v[240:241]
	v_pk_mul_f32 v[246:247], v[124:125], v[124:125]
	v_pk_mul_f32 v[234:235], v[124:125], v[190:191]
	v_pk_mul_f32 v[236:237], v[126:127], v[192:193]
	v_pk_fma_f32 v[246:247], v[126:127], v[126:127], v[246:247]
	v_pk_mul_f32 v[238:239], v[120:121], v[194:195]
	v_pk_fma_f32 v[246:247], v[120:121], v[120:121], v[246:247]
	v_pk_mul_f32 v[240:241], v[122:123], v[196:197]
	v_pk_fma_f32 v[246:247], v[122:123], v[122:123], v[246:247]
	v_cvt_pk_bf16_f32 v120, v234, v235
	v_cvt_pk_bf16_f32 v121, v236, v237
	v_cvt_pk_bf16_f32 v122, v238, v239
	v_cvt_pk_bf16_f32 v123, v240, v241
	v_add_f32_e32 v124, v246, v247
	v_add_co_u32_e32 v166, vcc, 0x10000, v168
	s_nop 1
	v_addc_co_u32_e32 v167, vcc, 0, v169, vcc
	global_store_dwordx4 v[166:167], v[120:123], off
	s_waitcnt vmcnt(7)
	v_lshlrev_b32_e32 v234, 16, v214
	v_lshlrev_b32_e32 v236, 16, v215
	v_lshlrev_b32_e32 v238, 16, v216
	v_lshlrev_b32_e32 v240, 16, v217
	v_and_b32_e32 v235, 0xffff0000, v214
	v_and_b32_e32 v237, 0xffff0000, v215
	v_and_b32_e32 v239, 0xffff0000, v216
	v_and_b32_e32 v241, 0xffff0000, v217
	v_pk_mul_f32 v[234:235], v[234:235], v[198:199]
	v_pk_mul_f32 v[236:237], v[236:237], v[200:201]
	v_pk_mul_f32 v[238:239], v[238:239], v[202:203]
	v_pk_mul_f32 v[240:241], v[240:241], v[204:205]
	v_pk_fma_f32 v[92:93], v[92:93], v[108:109], v[234:235]
	v_pk_fma_f32 v[94:95], v[94:95], v[110:111], v[236:237]
	v_pk_fma_f32 v[88:89], v[88:89], v[104:105], v[238:239]
	v_pk_fma_f32 v[90:91], v[90:91], v[106:107], v[240:241]
	v_pk_mul_f32 v[246:247], v[92:93], v[92:93]
	v_pk_mul_f32 v[234:235], v[92:93], v[190:191]
	v_pk_mul_f32 v[236:237], v[94:95], v[192:193]
	v_pk_fma_f32 v[246:247], v[94:95], v[94:95], v[246:247]
	v_pk_mul_f32 v[238:239], v[88:89], v[194:195]
	v_pk_fma_f32 v[246:247], v[88:89], v[88:89], v[246:247]
	v_pk_mul_f32 v[240:241], v[90:91], v[196:197]
	v_pk_fma_f32 v[246:247], v[90:91], v[90:91], v[246:247]
	v_cvt_pk_bf16_f32 v88, v234, v235
	v_cvt_pk_bf16_f32 v89, v236, v237
	v_cvt_pk_bf16_f32 v90, v238, v239
	v_cvt_pk_bf16_f32 v91, v240, v241
	v_add_f32_e32 v92, v246, v247
	v_add_co_u32_e32 v166, vcc, 0x20000, v168
	s_nop 1
	v_addc_co_u32_e32 v167, vcc, 0, v169, vcc
	global_store_dwordx4 v[166:167], v[88:91], off
	s_waitcnt vmcnt(7)
	v_lshlrev_b32_e32 v234, 16, v218
	v_lshlrev_b32_e32 v236, 16, v219
	v_lshlrev_b32_e32 v238, 16, v220
	v_lshlrev_b32_e32 v240, 16, v221
	v_and_b32_e32 v235, 0xffff0000, v218
	v_and_b32_e32 v237, 0xffff0000, v219
	v_and_b32_e32 v239, 0xffff0000, v220
	v_and_b32_e32 v241, 0xffff0000, v221
	v_pk_mul_f32 v[234:235], v[234:235], v[198:199]
	v_pk_mul_f32 v[236:237], v[236:237], v[200:201]
	v_pk_mul_f32 v[238:239], v[238:239], v[202:203]
	v_pk_mul_f32 v[240:241], v[240:241], v[204:205]
	v_pk_fma_f32 v[76:77], v[76:77], v[108:109], v[234:235]
	v_pk_fma_f32 v[78:79], v[78:79], v[110:111], v[236:237]
	v_pk_fma_f32 v[72:73], v[72:73], v[104:105], v[238:239]
	v_pk_fma_f32 v[74:75], v[74:75], v[106:107], v[240:241]
	v_pk_mul_f32 v[246:247], v[76:77], v[76:77]
	v_pk_mul_f32 v[234:235], v[76:77], v[190:191]
	v_pk_mul_f32 v[236:237], v[78:79], v[192:193]
	v_pk_fma_f32 v[246:247], v[78:79], v[78:79], v[246:247]
	v_pk_mul_f32 v[238:239], v[72:73], v[194:195]
	v_pk_fma_f32 v[246:247], v[72:73], v[72:73], v[246:247]
	v_pk_mul_f32 v[240:241], v[74:75], v[196:197]
	v_pk_fma_f32 v[246:247], v[74:75], v[74:75], v[246:247]
	v_cvt_pk_bf16_f32 v72, v234, v235
	v_cvt_pk_bf16_f32 v73, v236, v237
	v_cvt_pk_bf16_f32 v74, v238, v239
	v_cvt_pk_bf16_f32 v75, v240, v241
	v_add_f32_e32 v76, v246, v247
	v_add_co_u32_e32 v166, vcc, 0x30000, v168
	s_nop 1
	v_addc_co_u32_e32 v167, vcc, 0, v169, vcc
	global_store_dwordx4 v[166:167], v[72:75], off
	s_waitcnt vmcnt(7)
	v_lshlrev_b32_e32 v234, 16, v222
	v_lshlrev_b32_e32 v236, 16, v223
	v_lshlrev_b32_e32 v238, 16, v224
	v_lshlrev_b32_e32 v240, 16, v225
	v_and_b32_e32 v235, 0xffff0000, v222
	v_and_b32_e32 v237, 0xffff0000, v223
	v_and_b32_e32 v239, 0xffff0000, v224
	v_and_b32_e32 v241, 0xffff0000, v225
	v_pk_mul_f32 v[234:235], v[234:235], v[198:199]
	v_pk_mul_f32 v[236:237], v[236:237], v[200:201]
	v_pk_mul_f32 v[238:239], v[238:239], v[202:203]
	v_pk_mul_f32 v[240:241], v[240:241], v[204:205]
	v_pk_fma_f32 v[60:61], v[60:61], v[108:109], v[234:235]
	v_pk_fma_f32 v[62:63], v[62:63], v[110:111], v[236:237]
	v_pk_fma_f32 v[56:57], v[56:57], v[104:105], v[238:239]
	v_pk_fma_f32 v[58:59], v[58:59], v[106:107], v[240:241]
	v_pk_mul_f32 v[246:247], v[60:61], v[60:61]
	v_pk_mul_f32 v[234:235], v[60:61], v[190:191]
	v_pk_mul_f32 v[236:237], v[62:63], v[192:193]
	v_pk_fma_f32 v[246:247], v[62:63], v[62:63], v[246:247]
	v_pk_mul_f32 v[238:239], v[56:57], v[194:195]
	v_pk_fma_f32 v[246:247], v[56:57], v[56:57], v[246:247]
	v_pk_mul_f32 v[240:241], v[58:59], v[196:197]
	v_pk_fma_f32 v[246:247], v[58:59], v[58:59], v[246:247]
	v_cvt_pk_bf16_f32 v56, v234, v235
	v_cvt_pk_bf16_f32 v57, v236, v237
	v_cvt_pk_bf16_f32 v58, v238, v239
	v_cvt_pk_bf16_f32 v59, v240, v241
	v_add_f32_e32 v60, v246, v247
	v_add_co_u32_e32 v166, vcc, 0x80000, v168
	s_nop 1
	v_addc_co_u32_e32 v167, vcc, 0, v169, vcc
	global_store_dwordx4 v[166:167], v[56:59], off
	s_waitcnt vmcnt(7)
	v_lshlrev_b32_e32 v234, 16, v226
	v_lshlrev_b32_e32 v236, 16, v227
	v_lshlrev_b32_e32 v238, 16, v228
	v_lshlrev_b32_e32 v240, 16, v229
	v_and_b32_e32 v235, 0xffff0000, v226
	v_and_b32_e32 v237, 0xffff0000, v227
	v_and_b32_e32 v239, 0xffff0000, v228
	v_and_b32_e32 v241, 0xffff0000, v229
	v_pk_mul_f32 v[234:235], v[234:235], v[198:199]
	v_pk_mul_f32 v[236:237], v[236:237], v[200:201]
	v_pk_mul_f32 v[238:239], v[238:239], v[202:203]
	v_pk_mul_f32 v[240:241], v[240:241], v[204:205]
	v_pk_fma_f32 v[48:49], v[48:49], v[108:109], v[234:235]
	v_pk_fma_f32 v[50:51], v[50:51], v[110:111], v[236:237]
	v_pk_fma_f32 v[40:41], v[40:41], v[104:105], v[238:239]
	v_pk_fma_f32 v[42:43], v[42:43], v[106:107], v[240:241]
	v_pk_mul_f32 v[246:247], v[48:49], v[48:49]
	v_pk_mul_f32 v[234:235], v[48:49], v[190:191]
	v_pk_mul_f32 v[236:237], v[50:51], v[192:193]
	v_pk_fma_f32 v[246:247], v[50:51], v[50:51], v[246:247]
	v_pk_mul_f32 v[238:239], v[40:41], v[194:195]
	v_pk_fma_f32 v[246:247], v[40:41], v[40:41], v[246:247]
	v_pk_mul_f32 v[240:241], v[42:43], v[196:197]
	v_pk_fma_f32 v[246:247], v[42:43], v[42:43], v[246:247]
	v_cvt_pk_bf16_f32 v40, v234, v235
	v_cvt_pk_bf16_f32 v41, v236, v237
	v_cvt_pk_bf16_f32 v42, v238, v239
	v_cvt_pk_bf16_f32 v43, v240, v241
	v_add_f32_e32 v48, v246, v247
	v_add_co_u32_e32 v166, vcc, 0x90000, v168
	s_nop 1
	v_addc_co_u32_e32 v167, vcc, 0, v169, vcc
	global_store_dwordx4 v[166:167], v[40:43], off
	s_waitcnt vmcnt(7)
	v_lshlrev_b32_e32 v234, 16, v230
	v_lshlrev_b32_e32 v236, 16, v231
	v_lshlrev_b32_e32 v238, 16, v232
	v_lshlrev_b32_e32 v240, 16, v233
	v_and_b32_e32 v235, 0xffff0000, v230
	v_and_b32_e32 v237, 0xffff0000, v231
	v_and_b32_e32 v239, 0xffff0000, v232
	v_and_b32_e32 v241, 0xffff0000, v233
	v_pk_mul_f32 v[234:235], v[234:235], v[198:199]
	v_pk_mul_f32 v[236:237], v[236:237], v[200:201]
	v_pk_mul_f32 v[238:239], v[238:239], v[202:203]
	v_pk_mul_f32 v[240:241], v[240:241], v[204:205]
	v_pk_fma_f32 v[32:33], v[32:33], v[108:109], v[234:235]
	v_pk_fma_f32 v[34:35], v[34:35], v[110:111], v[236:237]
	v_pk_fma_f32 v[24:25], v[24:25], v[104:105], v[238:239]
	v_pk_fma_f32 v[26:27], v[26:27], v[106:107], v[240:241]
	v_pk_mul_f32 v[246:247], v[32:33], v[32:33]
	v_pk_mul_f32 v[234:235], v[32:33], v[190:191]
	v_pk_mul_f32 v[236:237], v[34:35], v[192:193]
	v_pk_fma_f32 v[246:247], v[34:35], v[34:35], v[246:247]
	v_pk_mul_f32 v[238:239], v[24:25], v[194:195]
	v_pk_fma_f32 v[246:247], v[24:25], v[24:25], v[246:247]
	v_pk_mul_f32 v[240:241], v[26:27], v[196:197]
	v_pk_fma_f32 v[246:247], v[26:27], v[26:27], v[246:247]
	v_cvt_pk_bf16_f32 v24, v234, v235
	v_cvt_pk_bf16_f32 v25, v236, v237
	v_cvt_pk_bf16_f32 v26, v238, v239
	v_cvt_pk_bf16_f32 v27, v240, v241
	v_add_f32_e32 v32, v246, v247
	v_add_co_u32_e32 v166, vcc, 0xa0000, v168
	s_nop 1
	v_addc_co_u32_e32 v167, vcc, 0, v169, vcc
	global_store_dwordx4 v[166:167], v[24:27], off
	s_waitcnt vmcnt(6)
	v_lshlrev_b32_e32 v234, 16, v206
	v_lshlrev_b32_e32 v236, 16, v207
	v_lshlrev_b32_e32 v238, 16, v208
	v_lshlrev_b32_e32 v240, 16, v209
	v_and_b32_e32 v235, 0xffff0000, v206
	v_and_b32_e32 v237, 0xffff0000, v207
	v_and_b32_e32 v239, 0xffff0000, v208
	v_and_b32_e32 v241, 0xffff0000, v209
	v_pk_mul_f32 v[234:235], v[234:235], v[198:199]
	v_pk_mul_f32 v[236:237], v[236:237], v[200:201]
	v_pk_mul_f32 v[238:239], v[238:239], v[202:203]
	v_pk_mul_f32 v[240:241], v[240:241], v[204:205]
	v_pk_fma_f32 v[16:17], v[16:17], v[108:109], v[234:235]
	v_pk_fma_f32 v[18:19], v[18:19], v[110:111], v[236:237]
	v_pk_fma_f32 v[8:9], v[8:9], v[104:105], v[238:239]
	v_pk_fma_f32 v[10:11], v[10:11], v[106:107], v[240:241]
	v_pk_mul_f32 v[246:247], v[16:17], v[16:17]
	v_pk_mul_f32 v[234:235], v[16:17], v[190:191]
	v_pk_mul_f32 v[236:237], v[18:19], v[192:193]
	v_pk_fma_f32 v[246:247], v[18:19], v[18:19], v[246:247]
	v_pk_mul_f32 v[238:239], v[8:9], v[194:195]
	v_pk_fma_f32 v[246:247], v[8:9], v[8:9], v[246:247]
	v_pk_mul_f32 v[240:241], v[10:11], v[196:197]
	v_pk_fma_f32 v[246:247], v[10:11], v[10:11], v[246:247]
	v_cvt_pk_bf16_f32 v8, v234, v235
	v_cvt_pk_bf16_f32 v9, v236, v237
	v_cvt_pk_bf16_f32 v10, v238, v239
	v_cvt_pk_bf16_f32 v11, v240, v241
	v_add_f32_e32 v16, v246, v247
	v_add_co_u32_e32 v166, vcc, 0xb0000, v168
	s_nop 1
	v_addc_co_u32_e32 v167, vcc, 0, v169, vcc
	global_store_dwordx4 v[166:167], v[8:11], off
	v_lshl_or_b32 v166, s96, 8, v174
	v_ashrrev_i32_e32 v167, 31, v166
	s_add_u32 s98, s68, 0x15e9c200
	s_addc_u32 s99, s69, 0
	v_lshl_add_u64 v[234:235], v[166:167], 2, s[98:99]
	global_load_dwordx4 v[190:193], v[234:235], off
	global_load_dwordx4 v[194:197], v[234:235], off offset:16
	v_readlane_b32 s98, v242, 47
	s_nop 3
	s_cmp_eq_u32 s98, 0
	s_mov_b32 s98, 0x15e9c200
	s_cselect_b32 s98, 0x15e98200, s98
	s_add_u32 s98, s68, s98
	s_addc_u32 s99, s69, 0
	v_lshl_add_u64 v[234:235], v[166:167], 2, s[98:99]
	global_load_dwordx4 v[198:201], v[234:235], off
	global_load_dwordx4 v[202:205], v[234:235], off offset:16
	v_mov_b32_e32 v166, v168
	v_mov_b32_e32 v167, v169
	global_load_dwordx4 v[206:209], v[166:167], off offset:256
	v_add_co_u32_e32 v166, vcc, 0x10000, v168
	s_nop 1
	v_addc_co_u32_e32 v167, vcc, 0, v169, vcc
	global_load_dwordx4 v[210:213], v[166:167], off offset:256
	v_add_co_u32_e32 v166, vcc, 0x20000, v168
	s_nop 1
	v_addc_co_u32_e32 v167, vcc, 0, v169, vcc
	global_load_dwordx4 v[214:217], v[166:167], off offset:256
	v_add_co_u32_e32 v166, vcc, 0x30000, v168
	s_nop 1
	v_addc_co_u32_e32 v167, vcc, 0, v169, vcc
	global_load_dwordx4 v[218:221], v[166:167], off offset:256
	v_add_co_u32_e32 v166, vcc, 0x80000, v168
	s_nop 1
	v_addc_co_u32_e32 v167, vcc, 0, v169, vcc
	global_load_dwordx4 v[222:225], v[166:167], off offset:256
	v_add_co_u32_e32 v166, vcc, 0x90000, v168
	s_nop 1
	v_addc_co_u32_e32 v167, vcc, 0, v169, vcc
	global_load_dwordx4 v[226:229], v[166:167], off offset:256
	v_add_co_u32_e32 v166, vcc, 0xa0000, v168
	s_nop 1
	v_addc_co_u32_e32 v167, vcc, 0, v169, vcc
	global_load_dwordx4 v[230:233], v[166:167], off offset:256
	s_waitcnt vmcnt(7)
	v_rcp_f32_e32 v198, v198
	v_rcp_f32_e32 v199, v199
	v_rcp_f32_e32 v200, v200
	v_rcp_f32_e32 v201, v201
	v_rcp_f32_e32 v202, v202
	v_rcp_f32_e32 v203, v203
	v_rcp_f32_e32 v204, v204
	v_rcp_f32_e32 v205, v205
	s_waitcnt vmcnt(6)
	v_lshlrev_b32_e32 v234, 16, v206
	v_lshlrev_b32_e32 v236, 16, v207
	v_lshlrev_b32_e32 v238, 16, v208
	v_lshlrev_b32_e32 v240, 16, v209
	v_and_b32_e32 v235, 0xffff0000, v206
	v_and_b32_e32 v237, 0xffff0000, v207
	v_and_b32_e32 v239, 0xffff0000, v208
	v_and_b32_e32 v241, 0xffff0000, v209
	v_pk_mul_f32 v[234:235], v[234:235], v[198:199]
	v_pk_mul_f32 v[236:237], v[236:237], v[200:201]
	v_pk_mul_f32 v[238:239], v[238:239], v[202:203]
	v_pk_mul_f32 v[240:241], v[240:241], v[204:205]
	v_pk_fma_f32 v[132:133], v[132:133], v[100:101], v[234:235]
	v_pk_fma_f32 v[134:135], v[134:135], v[102:103], v[236:237]
	v_pk_fma_f32 v[128:129], v[128:129], v[96:97], v[238:239]
	v_pk_fma_f32 v[130:131], v[130:131], v[98:99], v[240:241]
	v_pk_mul_f32 v[246:247], v[132:133], v[132:133]
	v_pk_mul_f32 v[234:235], v[132:133], v[190:191]
	v_pk_mul_f32 v[236:237], v[134:135], v[192:193]
	v_pk_fma_f32 v[246:247], v[134:135], v[134:135], v[246:247]
	v_pk_mul_f32 v[238:239], v[128:129], v[194:195]
	v_pk_fma_f32 v[246:247], v[128:129], v[128:129], v[246:247]
	v_pk_mul_f32 v[240:241], v[130:131], v[196:197]
	v_pk_fma_f32 v[246:247], v[130:131], v[130:131], v[246:247]
	v_cvt_pk_bf16_f32 v128, v234, v235
	v_cvt_pk_bf16_f32 v129, v236, v237
	v_cvt_pk_bf16_f32 v130, v238, v239
	v_cvt_pk_bf16_f32 v131, v240, v241
	v_add_f32_e32 v246, v246, v247
	s_nop 0
	v_add_f32_e32 v140, v140, v246
	v_mov_b32_e32 v166, v168
	v_mov_b32_e32 v167, v169
	global_store_dwordx4 v[166:167], v[128:131], off offset:256
	v_add_co_u32_e32 v166, vcc, 0xb0000, v168
	s_nop 1
	v_addc_co_u32_e32 v167, vcc, 0, v169, vcc
	global_load_dwordx4 v[206:209], v[166:167], off offset:256
	s_waitcnt vmcnt(7)
	v_lshlrev_b32_e32 v234, 16, v210
	v_lshlrev_b32_e32 v236, 16, v211
	v_lshlrev_b32_e32 v238, 16, v212
	v_lshlrev_b32_e32 v240, 16, v213
	v_and_b32_e32 v235, 0xffff0000, v210
	v_and_b32_e32 v237, 0xffff0000, v211
	v_and_b32_e32 v239, 0xffff0000, v212
	v_and_b32_e32 v241, 0xffff0000, v213
	v_pk_mul_f32 v[234:235], v[234:235], v[198:199]
	v_pk_mul_f32 v[236:237], v[236:237], v[200:201]
	v_pk_mul_f32 v[238:239], v[238:239], v[202:203]
	v_pk_mul_f32 v[240:241], v[240:241], v[204:205]
	v_pk_fma_f32 v[116:117], v[116:117], v[100:101], v[234:235]
	v_pk_fma_f32 v[118:119], v[118:119], v[102:103], v[236:237]
	v_pk_fma_f32 v[112:113], v[112:113], v[96:97], v[238:239]
	v_pk_fma_f32 v[114:115], v[114:115], v[98:99], v[240:241]
	v_pk_mul_f32 v[246:247], v[116:117], v[116:117]
	v_pk_mul_f32 v[234:235], v[116:117], v[190:191]
	v_pk_mul_f32 v[236:237], v[118:119], v[192:193]
	v_pk_fma_f32 v[246:247], v[118:119], v[118:119], v[246:247]
	v_pk_mul_f32 v[238:239], v[112:113], v[194:195]
	v_pk_fma_f32 v[246:247], v[112:113], v[112:113], v[246:247]
	v_pk_mul_f32 v[240:241], v[114:115], v[196:197]
	v_pk_fma_f32 v[246:247], v[114:115], v[114:115], v[246:247]
	v_cvt_pk_bf16_f32 v112, v234, v235
	v_cvt_pk_bf16_f32 v113, v236, v237
	v_cvt_pk_bf16_f32 v114, v238, v239
	v_cvt_pk_bf16_f32 v115, v240, v241
	v_add_f32_e32 v246, v246, v247
	s_nop 0
	v_add_f32_e32 v124, v124, v246
	v_add_co_u32_e32 v166, vcc, 0x10000, v168
	s_nop 1
	v_addc_co_u32_e32 v167, vcc, 0, v169, vcc
	global_store_dwordx4 v[166:167], v[112:115], off offset:256
	s_waitcnt vmcnt(7)
	v_lshlrev_b32_e32 v234, 16, v214
	v_lshlrev_b32_e32 v236, 16, v215
	v_lshlrev_b32_e32 v238, 16, v216
	v_lshlrev_b32_e32 v240, 16, v217
	v_and_b32_e32 v235, 0xffff0000, v214
	v_and_b32_e32 v237, 0xffff0000, v215
	v_and_b32_e32 v239, 0xffff0000, v216
	v_and_b32_e32 v241, 0xffff0000, v217
	v_pk_mul_f32 v[234:235], v[234:235], v[198:199]
	v_pk_mul_f32 v[236:237], v[236:237], v[200:201]
	v_pk_mul_f32 v[238:239], v[238:239], v[202:203]
	v_pk_mul_f32 v[240:241], v[240:241], v[204:205]
	v_pk_fma_f32 v[84:85], v[84:85], v[100:101], v[234:235]
	v_pk_fma_f32 v[86:87], v[86:87], v[102:103], v[236:237]
	v_pk_fma_f32 v[80:81], v[80:81], v[96:97], v[238:239]
	v_pk_fma_f32 v[82:83], v[82:83], v[98:99], v[240:241]
	v_pk_mul_f32 v[246:247], v[84:85], v[84:85]
	v_pk_mul_f32 v[234:235], v[84:85], v[190:191]
	v_pk_mul_f32 v[236:237], v[86:87], v[192:193]
	v_pk_fma_f32 v[246:247], v[86:87], v[86:87], v[246:247]
	v_pk_mul_f32 v[238:239], v[80:81], v[194:195]
	v_pk_fma_f32 v[246:247], v[80:81], v[80:81], v[246:247]
	v_pk_mul_f32 v[240:241], v[82:83], v[196:197]
	v_pk_fma_f32 v[246:247], v[82:83], v[82:83], v[246:247]
	v_cvt_pk_bf16_f32 v80, v234, v235
	v_cvt_pk_bf16_f32 v81, v236, v237
	v_cvt_pk_bf16_f32 v82, v238, v239
	v_cvt_pk_bf16_f32 v83, v240, v241
	v_add_f32_e32 v246, v246, v247
	s_nop 0
	v_add_f32_e32 v92, v92, v246
	v_add_co_u32_e32 v166, vcc, 0x20000, v168
	s_nop 1
	v_addc_co_u32_e32 v167, vcc, 0, v169, vcc
	global_store_dwordx4 v[166:167], v[80:83], off offset:256
	s_waitcnt vmcnt(7)
	v_lshlrev_b32_e32 v234, 16, v218
	v_lshlrev_b32_e32 v236, 16, v219
	v_lshlrev_b32_e32 v238, 16, v220
	v_lshlrev_b32_e32 v240, 16, v221
	v_and_b32_e32 v235, 0xffff0000, v218
	v_and_b32_e32 v237, 0xffff0000, v219
	v_and_b32_e32 v239, 0xffff0000, v220
	v_and_b32_e32 v241, 0xffff0000, v221
	v_pk_mul_f32 v[234:235], v[234:235], v[198:199]
	v_pk_mul_f32 v[236:237], v[236:237], v[200:201]
	v_pk_mul_f32 v[238:239], v[238:239], v[202:203]
	v_pk_mul_f32 v[240:241], v[240:241], v[204:205]
	v_pk_fma_f32 v[68:69], v[68:69], v[100:101], v[234:235]
	v_pk_fma_f32 v[70:71], v[70:71], v[102:103], v[236:237]
	v_pk_fma_f32 v[64:65], v[64:65], v[96:97], v[238:239]
	v_pk_fma_f32 v[66:67], v[66:67], v[98:99], v[240:241]
	v_pk_mul_f32 v[246:247], v[68:69], v[68:69]
	v_pk_mul_f32 v[234:235], v[68:69], v[190:191]
	v_pk_mul_f32 v[236:237], v[70:71], v[192:193]
	v_pk_fma_f32 v[246:247], v[70:71], v[70:71], v[246:247]
	v_pk_mul_f32 v[238:239], v[64:65], v[194:195]
	v_pk_fma_f32 v[246:247], v[64:65], v[64:65], v[246:247]
	v_pk_mul_f32 v[240:241], v[66:67], v[196:197]
	v_pk_fma_f32 v[246:247], v[66:67], v[66:67], v[246:247]
	v_cvt_pk_bf16_f32 v64, v234, v235
	v_cvt_pk_bf16_f32 v65, v236, v237
	v_cvt_pk_bf16_f32 v66, v238, v239
	v_cvt_pk_bf16_f32 v67, v240, v241
	v_add_f32_e32 v246, v246, v247
	s_nop 0
	v_add_f32_e32 v76, v76, v246
	v_add_co_u32_e32 v166, vcc, 0x30000, v168
	s_nop 1
	v_addc_co_u32_e32 v167, vcc, 0, v169, vcc
	global_store_dwordx4 v[166:167], v[64:67], off offset:256
	s_waitcnt vmcnt(7)
	v_lshlrev_b32_e32 v234, 16, v222
	v_lshlrev_b32_e32 v236, 16, v223
	v_lshlrev_b32_e32 v238, 16, v224
	v_lshlrev_b32_e32 v240, 16, v225
	v_and_b32_e32 v235, 0xffff0000, v222
	v_and_b32_e32 v237, 0xffff0000, v223
	v_and_b32_e32 v239, 0xffff0000, v224
	v_and_b32_e32 v241, 0xffff0000, v225
	v_pk_mul_f32 v[234:235], v[234:235], v[198:199]
	v_pk_mul_f32 v[236:237], v[236:237], v[200:201]
	v_pk_mul_f32 v[238:239], v[238:239], v[202:203]
	v_pk_mul_f32 v[240:241], v[240:241], v[204:205]
	v_pk_fma_f32 v[52:53], v[52:53], v[100:101], v[234:235]
	v_pk_fma_f32 v[54:55], v[54:55], v[102:103], v[236:237]
	v_pk_fma_f32 v[44:45], v[44:45], v[96:97], v[238:239]
	v_pk_fma_f32 v[46:47], v[46:47], v[98:99], v[240:241]
	v_pk_mul_f32 v[246:247], v[52:53], v[52:53]
	v_pk_mul_f32 v[234:235], v[52:53], v[190:191]
	v_pk_mul_f32 v[236:237], v[54:55], v[192:193]
	v_pk_fma_f32 v[246:247], v[54:55], v[54:55], v[246:247]
	v_pk_mul_f32 v[238:239], v[44:45], v[194:195]
	v_pk_fma_f32 v[246:247], v[44:45], v[44:45], v[246:247]
	v_pk_mul_f32 v[240:241], v[46:47], v[196:197]
	v_pk_fma_f32 v[246:247], v[46:47], v[46:47], v[246:247]
	v_cvt_pk_bf16_f32 v44, v234, v235
	v_cvt_pk_bf16_f32 v45, v236, v237
	v_cvt_pk_bf16_f32 v46, v238, v239
	v_cvt_pk_bf16_f32 v47, v240, v241
	v_add_f32_e32 v246, v246, v247
	s_nop 0
	v_add_f32_e32 v60, v60, v246
	v_add_co_u32_e32 v166, vcc, 0x80000, v168
	s_nop 1
	v_addc_co_u32_e32 v167, vcc, 0, v169, vcc
	global_store_dwordx4 v[166:167], v[44:47], off offset:256
	s_waitcnt vmcnt(7)
	v_lshlrev_b32_e32 v234, 16, v226
	v_lshlrev_b32_e32 v236, 16, v227
	v_lshlrev_b32_e32 v238, 16, v228
	v_lshlrev_b32_e32 v240, 16, v229
	v_and_b32_e32 v235, 0xffff0000, v226
	v_and_b32_e32 v237, 0xffff0000, v227
	v_and_b32_e32 v239, 0xffff0000, v228
	v_and_b32_e32 v241, 0xffff0000, v229
	v_pk_mul_f32 v[234:235], v[234:235], v[198:199]
	v_pk_mul_f32 v[236:237], v[236:237], v[200:201]
	v_pk_mul_f32 v[238:239], v[238:239], v[202:203]
	v_pk_mul_f32 v[240:241], v[240:241], v[204:205]
	v_pk_fma_f32 v[36:37], v[36:37], v[100:101], v[234:235]
	v_pk_fma_f32 v[38:39], v[38:39], v[102:103], v[236:237]
	v_pk_fma_f32 v[28:29], v[28:29], v[96:97], v[238:239]
	v_pk_fma_f32 v[30:31], v[30:31], v[98:99], v[240:241]
	v_pk_mul_f32 v[246:247], v[36:37], v[36:37]
	v_pk_mul_f32 v[234:235], v[36:37], v[190:191]
	v_pk_mul_f32 v[236:237], v[38:39], v[192:193]
	v_pk_fma_f32 v[246:247], v[38:39], v[38:39], v[246:247]
	v_pk_mul_f32 v[238:239], v[28:29], v[194:195]
	v_pk_fma_f32 v[246:247], v[28:29], v[28:29], v[246:247]
	v_pk_mul_f32 v[240:241], v[30:31], v[196:197]
	v_pk_fma_f32 v[246:247], v[30:31], v[30:31], v[246:247]
	v_cvt_pk_bf16_f32 v28, v234, v235
	v_cvt_pk_bf16_f32 v29, v236, v237
	v_cvt_pk_bf16_f32 v30, v238, v239
	v_cvt_pk_bf16_f32 v31, v240, v241
	v_add_f32_e32 v246, v246, v247
	s_nop 0
	v_add_f32_e32 v48, v48, v246
	v_add_co_u32_e32 v166, vcc, 0x90000, v168
	s_nop 1
	v_addc_co_u32_e32 v167, vcc, 0, v169, vcc
	global_store_dwordx4 v[166:167], v[28:31], off offset:256
	s_waitcnt vmcnt(7)
	v_lshlrev_b32_e32 v234, 16, v230
	v_lshlrev_b32_e32 v236, 16, v231
	v_lshlrev_b32_e32 v238, 16, v232
	v_lshlrev_b32_e32 v240, 16, v233
	v_and_b32_e32 v235, 0xffff0000, v230
	v_and_b32_e32 v237, 0xffff0000, v231
	v_and_b32_e32 v239, 0xffff0000, v232
	v_and_b32_e32 v241, 0xffff0000, v233
	v_pk_mul_f32 v[234:235], v[234:235], v[198:199]
	v_pk_mul_f32 v[236:237], v[236:237], v[200:201]
	v_pk_mul_f32 v[238:239], v[238:239], v[202:203]
	v_pk_mul_f32 v[240:241], v[240:241], v[204:205]
	v_pk_fma_f32 v[20:21], v[20:21], v[100:101], v[234:235]
	v_pk_fma_f32 v[22:23], v[22:23], v[102:103], v[236:237]
	v_pk_fma_f32 v[12:13], v[12:13], v[96:97], v[238:239]
	v_pk_fma_f32 v[14:15], v[14:15], v[98:99], v[240:241]
	v_pk_mul_f32 v[246:247], v[20:21], v[20:21]
	v_pk_mul_f32 v[234:235], v[20:21], v[190:191]
	v_pk_mul_f32 v[236:237], v[22:23], v[192:193]
	v_pk_fma_f32 v[246:247], v[22:23], v[22:23], v[246:247]
	v_pk_mul_f32 v[238:239], v[12:13], v[194:195]
	v_pk_fma_f32 v[246:247], v[12:13], v[12:13], v[246:247]
	v_pk_mul_f32 v[240:241], v[14:15], v[196:197]
	v_pk_fma_f32 v[246:247], v[14:15], v[14:15], v[246:247]
	v_cvt_pk_bf16_f32 v12, v234, v235
	v_cvt_pk_bf16_f32 v13, v236, v237
	v_cvt_pk_bf16_f32 v14, v238, v239
	v_cvt_pk_bf16_f32 v15, v240, v241
	v_add_f32_e32 v246, v246, v247
	s_nop 0
	v_add_f32_e32 v32, v32, v246
	v_add_co_u32_e32 v166, vcc, 0xa0000, v168
	s_nop 1
	v_addc_co_u32_e32 v167, vcc, 0, v169, vcc
	global_store_dwordx4 v[166:167], v[12:15], off offset:256
	s_waitcnt vmcnt(6)
	v_lshlrev_b32_e32 v234, 16, v206
	v_lshlrev_b32_e32 v236, 16, v207
	v_lshlrev_b32_e32 v238, 16, v208
	v_lshlrev_b32_e32 v240, 16, v209
	v_and_b32_e32 v235, 0xffff0000, v206
	v_and_b32_e32 v237, 0xffff0000, v207
	v_and_b32_e32 v239, 0xffff0000, v208
	v_and_b32_e32 v241, 0xffff0000, v209
	v_pk_mul_f32 v[234:235], v[234:235], v[198:199]
	v_pk_mul_f32 v[236:237], v[236:237], v[200:201]
	v_pk_mul_f32 v[238:239], v[238:239], v[202:203]
	v_pk_mul_f32 v[240:241], v[240:241], v[204:205]
	v_pk_fma_f32 v[4:5], v[4:5], v[100:101], v[234:235]
	v_pk_fma_f32 v[6:7], v[6:7], v[102:103], v[236:237]
	v_pk_fma_f32 v[0:1], v[0:1], v[96:97], v[238:239]
	v_pk_fma_f32 v[2:3], v[2:3], v[98:99], v[240:241]
	v_pk_mul_f32 v[246:247], v[4:5], v[4:5]
	v_pk_mul_f32 v[234:235], v[4:5], v[190:191]
	v_pk_mul_f32 v[236:237], v[6:7], v[192:193]
	v_pk_fma_f32 v[246:247], v[6:7], v[6:7], v[246:247]
	v_pk_mul_f32 v[238:239], v[0:1], v[194:195]
	v_pk_fma_f32 v[246:247], v[0:1], v[0:1], v[246:247]
	v_pk_mul_f32 v[240:241], v[2:3], v[196:197]
	v_pk_fma_f32 v[246:247], v[2:3], v[2:3], v[246:247]
	v_cvt_pk_bf16_f32 v0, v234, v235
	v_cvt_pk_bf16_f32 v1, v236, v237
	v_cvt_pk_bf16_f32 v2, v238, v239
	v_cvt_pk_bf16_f32 v3, v240, v241
	v_add_f32_e32 v246, v246, v247
	s_nop 0
	v_add_f32_e32 v16, v16, v246
	v_add_co_u32_e32 v166, vcc, 0xb0000, v168
	s_nop 1
	v_addc_co_u32_e32 v167, vcc, 0, v169, vcc
	global_store_dwordx4 v[166:167], v[0:3], off offset:256
	v_readlane_b32 s98, v242, 47
	s_nop 3
	s_cmp_eq_u32 s98, 0
	s_cbranch_scc0 .Lfe_tail
	v_and_b32_e32 v234, 63, v175
	v_xor_b32_e32 v235, 16, v234
	v_xor_b32_e32 v236, 32, v234
	v_lshlrev_b32_e32 v235, 2, v235
	v_lshlrev_b32_e32 v236, 2, v236
	ds_bpermute_b32 v206, v235, v140
	ds_bpermute_b32 v207, v235, v124
	ds_bpermute_b32 v208, v235, v92
	ds_bpermute_b32 v209, v235, v76
	ds_bpermute_b32 v210, v235, v60
	ds_bpermute_b32 v211, v235, v48
	ds_bpermute_b32 v212, v235, v32
	ds_bpermute_b32 v213, v235, v16
	s_waitcnt lgkmcnt(0)
	v_add_f32_e32 v140, v140, v206
	v_add_f32_e32 v124, v124, v207
	v_add_f32_e32 v92, v92, v208
	v_add_f32_e32 v76, v76, v209
	v_add_f32_e32 v60, v60, v210
	v_add_f32_e32 v48, v48, v211
	v_add_f32_e32 v32, v32, v212
	v_add_f32_e32 v16, v16, v213
	ds_bpermute_b32 v206, v236, v140
	ds_bpermute_b32 v207, v236, v124
	ds_bpermute_b32 v208, v236, v92
	ds_bpermute_b32 v209, v236, v76
	ds_bpermute_b32 v210, v236, v60
	ds_bpermute_b32 v211, v236, v48
	ds_bpermute_b32 v212, v236, v32
	ds_bpermute_b32 v213, v236, v16
	s_waitcnt lgkmcnt(0)
	v_add_f32_e32 v140, v140, v206
	v_add_f32_e32 v124, v124, v207
	v_add_f32_e32 v92, v92, v208
	v_add_f32_e32 v76, v76, v209
	v_add_f32_e32 v60, v60, v210
	v_add_f32_e32 v48, v48, v211
	v_add_f32_e32 v32, v32, v212
	v_add_f32_e32 v16, v16, v213
	s_add_u32 s98, s68, 0x15ec4800
	s_addc_u32 s99, s69, 0
	v_cmp_gt_u32_e32 vcc, 16, v234
	s_and_saveexec_b64 s[100:101], vcc
	v_add_u32_e32 v214, 0, v170
	v_lshlrev_b32_e32 v214, 2, v214
	v_add_u32_e32 v215, 16, v170
	v_lshlrev_b32_e32 v215, 2, v215
	v_add_u32_e32 v216, 32, v170
	v_lshlrev_b32_e32 v216, 2, v216
	v_add_u32_e32 v217, 48, v170
	v_lshlrev_b32_e32 v217, 2, v217
	v_add_u32_e32 v218, 128, v170
	v_lshlrev_b32_e32 v218, 2, v218
	v_add_u32_e32 v219, 144, v170
	v_lshlrev_b32_e32 v219, 2, v219
	v_add_u32_e32 v220, 160, v170
	v_lshlrev_b32_e32 v220, 2, v220
	v_add_u32_e32 v221, 176, v170
	v_lshlrev_b32_e32 v221, 2, v221
	global_atomic_add_f32 v214, v140, s[98:99]
	global_atomic_add_f32 v215, v124, s[98:99]
	global_atomic_add_f32 v216, v92, s[98:99]
	global_atomic_add_f32 v217, v76, s[98:99]
	global_atomic_add_f32 v218, v60, s[98:99]
	global_atomic_add_f32 v219, v48, s[98:99]
	global_atomic_add_f32 v220, v32, s[98:99]
	global_atomic_add_f32 v221, v16, s[98:99]
	s_or_b64 exec, exec, s[100:101]
.Lfe_tail:
	s_mov_b64 s[10:11], 0xb0000
	s_andn2_b64 vcc, exec, s[40:41]
	s_cbranch_vccnz .LBB0_705
	s_andn2_b64 vcc, exec, s[42:43]
	s_cbranch_vccnz .LBB0_704
	s_barrier
	s_branch .LBB0_704
